# grid barrier: every workgroup (leaders and non-leaders) polls the cross-XCD arrival counter until it reaches (gen+1)*nx, removing the release-generation hop; attention staging edits kept
# speedup vs baseline: 1.0011x; 1.0011x over previous
.LBB0_130:
	s_or_b64 exec, exec, s[26:27]
	v_cvt_f32_u32_e32 v5, v3
	s_waitcnt vmcnt(0)
	v_readfirstlane_b32 s0, v4
	v_sub_u32_e32 v4, 0, v3
	v_rcp_iflag_f32_e32 v5, v5
	v_add_u32_e32 v6, s0, v0
	v_mul_f32_e32 v5, 0x4f7ffffe, v5
	v_cvt_u32_f32_e32 v5, v5
	v_mul_lo_u32 v0, v4, v5
	v_mul_hi_u32 v0, v5, v0
	v_add_u32_e32 v0, v5, v0
	v_mul_hi_u32 v0, v6, v0
	v_mul_lo_u32 v4, v0, v3
	v_sub_u32_e32 v4, v6, v4
	v_add_u32_e32 v5, 1, v0
	v_cmp_ge_u32_e32 vcc, v4, v3
	s_nop 1
	v_cndmask_b32_e32 v0, v0, v5, vcc
	v_sub_u32_e32 v5, v4, v3
	v_cndmask_b32_e32 v4, v4, v5, vcc
	v_add_u32_e32 v5, 1, v0
	v_cmp_ge_u32_e32 vcc, v4, v3
	v_add_u32_e32 v4, 1, v6
	s_nop 0
	v_cndmask_b32_e32 v0, v0, v5, vcc
	v_mul_lo_u32 v5, v3, v0
	v_add_u32_e32 v3, v5, v3
	v_cmp_ne_u32_e32 vcc, v4, v3
	s_and_saveexec_b64 s[14:15], vcc
	s_xor_b64 s[26:27], exec, s[14:15]
	s_cbranch_execz .LBB0_144
	v_readlane_b32 s14, v251, 50
	v_readlane_b32 s15, v251, 51
	s_waitcnt lgkmcnt(0)
	s_nop 3
	v_add_u32_e32 v0, 1, v0
	v_mul_lo_u32 v0, v0, v2
	global_load_dword v2, v1, s[14:15] sc1
	s_waitcnt vmcnt(0)
	v_cmp_lt_u32_e32 vcc, v2, v0
	s_and_saveexec_b64 s[28:29], vcc
	s_cbranch_execz .LBB0_143
	s_mov_b32 s0, 1
	s_mov_b64 s[30:31], 0
	s_branch .LBB0_134

.LBB0_138:
	v_readlane_b32 s14, v251, 50
	v_readlane_b32 s15, v251, 51
	s_add_i32 s0, s0, 1
	s_mov_b64 s[38:39], -1
	s_nop 2
	global_load_dword v2, v1, s[14:15] sc1
	s_waitcnt vmcnt(0)
	v_cmp_ge_u32_e32 vcc, v2, v0
	s_orn2_b64 s[36:37], vcc, exec
	s_branch .LBB0_133

.LBB0_147:
	s_or_b64 exec, exec, s[28:29]
	v_cvt_f32_u32_e32 v4, v2
	s_waitcnt vmcnt(0)
	v_readfirstlane_b32 s0, v3
	v_readlane_b32 s14, v251, 52
	v_readlane_b32 s15, v251, 53
	v_rcp_iflag_f32_e32 v4, v4
	v_add_u32_e32 v0, s0, v0
	v_add_u32_e32 v5, 1, v0
	s_mov_b64 s[28:29], -1
	v_mul_f32_e32 v3, 0x4f7ffffe, v4
	v_cvt_u32_f32_e32 v3, v3
	v_sub_u32_e32 v4, 0, v2
	v_mul_lo_u32 v4, v4, v3
	v_mul_hi_u32 v4, v3, v4
	v_add_u32_e32 v3, v3, v4
	v_mul_hi_u32 v3, v0, v3
	v_mul_lo_u32 v4, v3, v2
	v_sub_u32_e32 v0, v0, v4
	v_add_u32_e32 v6, 1, v3
	v_cmp_ge_u32_e32 vcc, v0, v2
	v_sub_u32_e32 v4, v0, v2
	s_nop 0
	v_cndmask_b32_e32 v3, v3, v6, vcc
	v_cndmask_b32_e32 v0, v0, v4, vcc
	v_add_u32_e32 v4, 1, v3
	v_cmp_ge_u32_e32 vcc, v0, v2
	s_nop 1
	v_cndmask_b32_e32 v0, v3, v4, vcc
	v_mul_lo_u32 v3, v2, v0
	v_add_u32_e32 v2, v3, v2
	v_mov_b32_e32 v0, v2
	v_cmp_ne_u32_e32 vcc, v5, v2
	v_mov_b64_e32 v[2:3], s[14:15]
	s_and_saveexec_b64 s[26:27], vcc
	s_cbranch_execz .LBB0_159
	v_readlane_b32 s14, v251, 50
	v_readlane_b32 s15, v251, 51
	s_mov_b64 s[30:31], 0
	s_nop 3
	global_load_dword v2, v1, s[14:15] sc1
	s_waitcnt vmcnt(0)
	v_cmp_lt_u32_e32 vcc, v2, v0
	s_and_saveexec_b64 s[28:29], vcc
	s_cbranch_execz .LBB0_158
	s_mov_b32 s0, 1
	s_branch .LBB0_151

.LBB0_275:
	s_or_b64 exec, exec, s[28:29]
	s_waitcnt vmcnt(0)
	v_readfirstlane_b32 s0, v3
	v_sub_u32_e32 v4, 0, v2
	v_readlane_b32 s14, v251, 52
	v_add_u32_e32 v3, s0, v0
	v_cvt_f32_u32_e32 v0, v2
	v_readlane_b32 s15, v251, 53
	s_mov_b64 s[28:29], -1
	v_rcp_iflag_f32_e32 v0, v0
	s_nop 0
	v_mul_f32_e32 v0, 0x4f7ffffe, v0
	v_cvt_u32_f32_e32 v0, v0
	v_mul_lo_u32 v4, v4, v0
	v_mul_hi_u32 v4, v0, v4
	v_add_u32_e32 v0, v0, v4
	v_mul_hi_u32 v0, v3, v0
	v_mul_lo_u32 v4, v0, v2
	v_sub_u32_e32 v4, v3, v4
	v_cmp_ge_u32_e32 vcc, v4, v2
	v_add_u32_e32 v5, 1, v0
	v_add_u32_e32 v3, 1, v3
	v_cndmask_b32_e32 v0, v0, v5, vcc
	v_sub_u32_e32 v5, v4, v2
	v_cndmask_b32_e32 v4, v4, v5, vcc
	v_cmp_ge_u32_e32 vcc, v4, v2
	v_add_u32_e32 v4, 1, v0
	s_nop 0
	v_cndmask_b32_e32 v0, v0, v4, vcc
	v_mul_lo_u32 v4, v2, v0
	v_add_u32_e32 v2, v4, v2
	v_mov_b32_e32 v0, v2
	v_cmp_ne_u32_e32 vcc, v3, v2
	v_mov_b64_e32 v[2:3], s[14:15]
	s_and_saveexec_b64 s[26:27], vcc
	s_cbranch_execz .LBB0_287
	v_readlane_b32 s14, v251, 50
	v_readlane_b32 s15, v251, 51
	s_mov_b64 s[30:31], 0
	s_nop 3
	global_load_dword v2, v1, s[14:15] sc1
	s_waitcnt vmcnt(0)
	v_cmp_lt_u32_e32 vcc, v2, v0
	s_and_saveexec_b64 s[28:29], vcc
	s_cbranch_execz .LBB0_286
	s_mov_b32 s0, 1
	s_branch .LBB0_279
